# baseline (speedup 1.0000x reference)
.LBB0_363:
	s_mul_hi_i32 s12, s55, 0x2aaaaaab
	s_lshr_b32 s13, s12, 31
	s_ashr_i32 s12, s12, 4
	s_add_i32 s12, s12, s13
	s_lshl_b32 s14, s55, 8
	s_mul_i32 s13, s12, 0xffffffa0
	s_lshl_b32 s12, s12, 11
	s_and_b32 s14, s14, 0x700
	s_or_b32 s16, s12, s14
	s_add_i32 s13, s13, s55
	s_or_b32 s18, s16, 0x80
	s_lshl_b32 s12, s13, 5
	s_ashr_i32 s19, s18, 31
	s_and_b32 s12, s12, 0xffffff00
	s_lshl_b64 s[14:15], s[18:19], 10
	s_lshl_b64 s[18:19], s[18:19], 11
	s_add_u32 s20, s22, s18
	s_addc_u32 s21, s23, s19
	s_ashr_i32 s13, s12, 31
	s_lshl_b64 s[18:19], s[12:13], 11
	s_add_u32 s56, s24, s18
	s_addc_u32 s57, s25, s19
	s_ashr_i32 s17, s16, 31
	s_barrier
	s_barrier
	s_lshl_b64 s[18:19], s[16:17], 11
	ds_read_b128 v[2:5], v137
	ds_read_b128 v[6:9], v137 offset:1024
	ds_read_b128 v[10:13], v137 offset:2048
	ds_read_b128 v[14:17], v137 offset:3072
	s_add_u32 s17, s22, s18
	s_addc_u32 s58, s23, s19
	s_or_b32 s18, s12, 0x80
	s_ashr_i32 s19, s18, 31
	s_lshl_b64 s[18:19], s[18:19], 11
	s_add_u32 s59, s24, s18
	s_addc_u32 s60, s25, s19
	ds_read_b128 v[18:21], v136 offset:7168
	ds_read_b128 v[22:25], v136 offset:6144
	ds_read_b128 v[26:29], v136 offset:5120
	ds_read_b128 v[30:33], v136 offset:4096
	ds_read_b128 v[34:37], v136 offset:3072
	ds_read_b128 v[38:41], v136 offset:2048
	ds_read_b128 v[42:45], v136 offset:1024
	ds_read_b128 v[46:49], v136
	s_waitcnt lgkmcnt(8)
	s_barrier
	s_waitcnt lgkmcnt(0)
	s_setprio 3
	s_waitcnt lgkmcnt(0)
	v_mfma_f32_16x16x32_bf16 v[50:53], v[46:49], v[2:5], 0
	v_mfma_f32_16x16x32_bf16 v[54:57], v[46:49], v[10:13], 0
	v_mfma_f32_16x16x32_bf16 v[58:61], v[38:41], v[2:5], 0
	v_mfma_f32_16x16x32_bf16 v[62:65], v[38:41], v[10:13], 0
	v_mfma_f32_16x16x32_bf16 v[66:69], v[30:33], v[2:5], 0
	v_mfma_f32_16x16x32_bf16 v[70:73], v[30:33], v[10:13], 0
	v_mfma_f32_16x16x32_bf16 v[74:77], v[22:25], v[2:5], 0
	v_mfma_f32_16x16x32_bf16 v[78:81], v[22:25], v[10:13], 0
	v_mfma_f32_16x16x32_bf16 v[50:53], v[42:45], v[6:9], v[50:53]
	v_mfma_f32_16x16x32_bf16 v[54:57], v[42:45], v[14:17], v[54:57]
	v_mfma_f32_16x16x32_bf16 v[58:61], v[34:37], v[6:9], v[58:61]
	v_mfma_f32_16x16x32_bf16 v[62:65], v[34:37], v[14:17], v[62:65]
	v_mfma_f32_16x16x32_bf16 v[66:69], v[26:29], v[6:9], v[66:69]
	v_mfma_f32_16x16x32_bf16 v[70:73], v[26:29], v[14:17], v[70:73]
	v_mfma_f32_16x16x32_bf16 v[74:77], v[18:21], v[6:9], v[74:77]
	v_mfma_f32_16x16x32_bf16 v[78:81], v[18:21], v[14:17], v[78:81]
	s_setprio 0
	s_barrier
	s_add_u32 s18, s56, 0x100
	s_addc_u32 s19, s57, 0
	s_mov_b32 m0, s28
	ds_read_b128 v[82:85], v137 offset:16384
	ds_read_b128 v[86:89], v137 offset:17408
	ds_read_b128 v[90:93], v137 offset:18432
	ds_read_b128 v[94:97], v137 offset:19456
	s_nop 0
	v_lshl_add_u64 v[98:99], s[18:19], 0, v[130:131]
	global_load_lds_dwordx4 v[98:99], off
	v_lshl_add_u64 v[98:99], s[18:19], 0, v[132:133]
	s_mov_b32 m0, s29
	s_nop 0
	global_load_lds_dwordx4 v[98:99], off
	s_barrier
	s_waitcnt lgkmcnt(0)
	s_setprio 3
	s_waitcnt lgkmcnt(0)
	v_mfma_f32_16x16x32_bf16 v[98:101], v[46:49], v[82:85], 0
	v_mfma_f32_16x16x32_bf16 v[46:49], v[46:49], v[90:93], 0
	v_mfma_f32_16x16x32_bf16 v[98:101], v[42:45], v[86:89], v[98:101]
	v_mfma_f32_16x16x32_bf16 v[42:45], v[42:45], v[94:97], v[46:49]
	v_mfma_f32_16x16x32_bf16 v[46:49], v[38:41], v[82:85], 0
	v_mfma_f32_16x16x32_bf16 v[38:41], v[38:41], v[90:93], 0
	v_mfma_f32_16x16x32_bf16 v[46:49], v[34:37], v[86:89], v[46:49]
	v_mfma_f32_16x16x32_bf16 v[34:37], v[34:37], v[94:97], v[38:41]
	v_mfma_f32_16x16x32_bf16 v[38:41], v[30:33], v[82:85], 0
	v_mfma_f32_16x16x32_bf16 v[30:33], v[30:33], v[90:93], 0
	v_mfma_f32_16x16x32_bf16 v[38:41], v[26:29], v[86:89], v[38:41]
	v_mfma_f32_16x16x32_bf16 v[102:105], v[26:29], v[94:97], v[30:33]
	v_mfma_f32_16x16x32_bf16 v[26:29], v[22:25], v[82:85], 0
	v_mfma_f32_16x16x32_bf16 v[22:25], v[22:25], v[90:93], 0
	v_mfma_f32_16x16x32_bf16 v[106:109], v[18:21], v[86:89], v[26:29]
	v_mfma_f32_16x16x32_bf16 v[110:113], v[18:21], v[94:97], v[22:25]
	s_setprio 0
	s_add_u32 s18, s17, 0x100
	s_addc_u32 s19, s58, 0
	s_mov_b32 m0, s27
	s_barrier
	ds_read_b128 v[18:21], v136 offset:16384
	ds_read_b128 v[22:25], v136 offset:17408
	ds_read_b128 v[26:29], v136 offset:18432
	ds_read_b128 v[30:33], v136 offset:19456
	ds_read_b128 v[114:117], v136 offset:20480
	ds_read_b128 v[118:121], v136 offset:21504
	ds_read_b128 v[122:125], v136 offset:22528
	ds_read_b128 v[126:129], v136 offset:23552
	s_nop 0
	v_lshl_add_u64 v[134:135], s[18:19], 0, v[130:131]
	global_load_lds_dwordx4 v[134:135], off
	v_lshl_add_u64 v[134:135], s[18:19], 0, v[132:133]
	s_mov_b32 m0, s30
	s_nop 0
	global_load_lds_dwordx4 v[134:135], off
	s_barrier
	s_waitcnt lgkmcnt(0)
	s_setprio 3
	s_waitcnt lgkmcnt(0)
	v_mfma_f32_16x16x32_bf16 v[142:145], v[18:21], v[2:5], 0
	v_mfma_f32_16x16x32_bf16 v[150:153], v[26:29], v[2:5], 0
	v_mfma_f32_16x16x32_bf16 v[158:161], v[114:117], v[2:5], 0
	v_mfma_f32_16x16x32_bf16 v[2:5], v[122:125], v[2:5], 0
	v_mfma_f32_16x16x32_bf16 v[146:149], v[18:21], v[10:13], 0
	v_mfma_f32_16x16x32_bf16 v[154:157], v[26:29], v[10:13], 0
	v_mfma_f32_16x16x32_bf16 v[162:165], v[114:117], v[10:13], 0
	v_mfma_f32_16x16x32_bf16 v[166:169], v[126:129], v[6:9], v[2:5]
	v_mfma_f32_16x16x32_bf16 v[2:5], v[122:125], v[10:13], 0
	v_mfma_f32_16x16x32_bf16 v[142:145], v[22:25], v[6:9], v[142:145]
	v_mfma_f32_16x16x32_bf16 v[146:149], v[22:25], v[14:17], v[146:149]
	v_mfma_f32_16x16x32_bf16 v[150:153], v[30:33], v[6:9], v[150:153]
	v_mfma_f32_16x16x32_bf16 v[154:157], v[30:33], v[14:17], v[154:157]
	v_mfma_f32_16x16x32_bf16 v[158:161], v[118:121], v[6:9], v[158:161]
	v_mfma_f32_16x16x32_bf16 v[162:165], v[118:121], v[14:17], v[162:165]
	v_mfma_f32_16x16x32_bf16 v[170:173], v[126:129], v[14:17], v[2:5]
	s_setprio 0
	s_barrier
	s_add_u32 s18, s59, 0x100
	s_addc_u32 s19, s60, 0
	s_mov_b32 m0, s31
	s_nop 0
	v_lshl_add_u64 v[2:3], s[18:19], 0, v[130:131]
	global_load_lds_dwordx4 v[2:3], off
	v_lshl_add_u64 v[2:3], s[18:19], 0, v[132:133]
	s_mov_b32 m0, s33
	s_nop 0
	global_load_lds_dwordx4 v[2:3], off
	s_waitcnt vmcnt(22)
	s_barrier
	s_setprio 3
	v_mfma_f32_16x16x32_bf16 v[2:5], v[18:21], v[82:85], 0
	v_mfma_f32_16x16x32_bf16 v[174:177], v[22:25], v[86:89], v[2:5]
	v_mfma_f32_16x16x32_bf16 v[2:5], v[18:21], v[90:93], 0
	v_mfma_f32_16x16x32_bf16 v[178:181], v[22:25], v[94:97], v[2:5]
	v_mfma_f32_16x16x32_bf16 v[2:5], v[26:29], v[82:85], 0
	v_mfma_f32_16x16x32_bf16 v[182:185], v[30:33], v[86:89], v[2:5]
	v_mfma_f32_16x16x32_bf16 v[2:5], v[26:29], v[90:93], 0
	v_mfma_f32_16x16x32_bf16 v[186:189], v[30:33], v[94:97], v[2:5]
	v_mfma_f32_16x16x32_bf16 v[2:5], v[114:117], v[82:85], 0
	v_mfma_f32_16x16x32_bf16 v[190:193], v[118:121], v[86:89], v[2:5]
	v_mfma_f32_16x16x32_bf16 v[2:5], v[114:117], v[90:93], 0
	v_mfma_f32_16x16x32_bf16 v[194:197], v[118:121], v[94:97], v[2:5]
	v_mfma_f32_16x16x32_bf16 v[2:5], v[122:125], v[82:85], 0
	v_mfma_f32_16x16x32_bf16 v[198:201], v[126:129], v[86:89], v[2:5]
	v_mfma_f32_16x16x32_bf16 v[2:5], v[122:125], v[90:93], 0
	v_mfma_f32_16x16x32_bf16 v[202:205], v[126:129], v[94:97], v[2:5]
	s_setprio 0
	s_barrier
	ds_read_b128 v[114:117], v137 offset:32768
	ds_read_b128 v[118:121], v137 offset:33792
	ds_read_b128 v[122:125], v137 offset:34816
	ds_read_b128 v[126:129], v137 offset:35840
	s_add_u32 s18, s20, 0x100
	s_addc_u32 s19, s21, 0
	s_mov_b32 m0, s34
	ds_read_b128 v[82:85], v136 offset:32768
	ds_read_b128 v[86:89], v136 offset:33792
	ds_read_b128 v[90:93], v136 offset:34816
	ds_read_b128 v[94:97], v136 offset:35840
	ds_read_b128 v[212:215], v136 offset:36864
	ds_read_b128 v[216:219], v136 offset:37888
	ds_read_b128 v[220:223], v136 offset:38912
	ds_read_b128 v[224:227], v136 offset:39936
	s_nop 0
	v_lshl_add_u64 v[2:3], s[18:19], 0, v[130:131]
	global_load_lds_dwordx4 v[2:3], off
	v_lshl_add_u64 v[2:3], s[18:19], 0, v[132:133]
	s_mov_b32 m0, s35
	s_nop 0
	global_load_lds_dwordx4 v[2:3], off
	s_waitcnt lgkmcnt(8)
	s_barrier
	s_waitcnt lgkmcnt(0)
	s_setprio 3
	s_waitcnt lgkmcnt(0)
	v_mfma_f32_16x16x32_bf16 v[2:5], v[82:85], v[114:117], v[50:53]
	v_mfma_f32_16x16x32_bf16 v[30:33], v[86:89], v[118:121], v[2:5]
	v_mfma_f32_16x16x32_bf16 v[2:5], v[82:85], v[122:125], v[54:57]
	v_mfma_f32_16x16x32_bf16 v[26:29], v[86:89], v[126:129], v[2:5]
	v_mfma_f32_16x16x32_bf16 v[2:5], v[90:93], v[114:117], v[58:61]
	v_mfma_f32_16x16x32_bf16 v[22:25], v[94:97], v[118:121], v[2:5]
	v_mfma_f32_16x16x32_bf16 v[2:5], v[90:93], v[122:125], v[62:65]
	v_mfma_f32_16x16x32_bf16 v[18:21], v[94:97], v[126:129], v[2:5]
	v_mfma_f32_16x16x32_bf16 v[2:5], v[212:215], v[114:117], v[66:69]
	v_mfma_f32_16x16x32_bf16 v[14:17], v[216:219], v[118:121], v[2:5]
	v_mfma_f32_16x16x32_bf16 v[2:5], v[212:215], v[122:125], v[70:73]
	v_mfma_f32_16x16x32_bf16 v[10:13], v[216:219], v[126:129], v[2:5]
	v_mfma_f32_16x16x32_bf16 v[2:5], v[220:223], v[114:117], v[74:77]
	v_mfma_f32_16x16x32_bf16 v[6:9], v[224:227], v[118:121], v[2:5]
	v_mfma_f32_16x16x32_bf16 v[2:5], v[220:223], v[122:125], v[78:81]
	v_mfma_f32_16x16x32_bf16 v[2:5], v[224:227], v[126:129], v[2:5]
	s_setprio 0
	s_barrier
	s_add_u32 s18, s56, 0x180
	s_addc_u32 s19, s57, 0
	s_mov_b32 m0, s36
	ds_read_b128 v[228:231], v137 offset:49152
	ds_read_b128 v[232:235], v137 offset:50176
	ds_read_b128 v[236:239], v137 offset:51200
	ds_read_b128 v[240:243], v137 offset:52224
	s_nop 0
	v_lshl_add_u64 v[50:51], s[18:19], 0, v[130:131]
	global_load_lds_dwordx4 v[50:51], off
	v_lshl_add_u64 v[50:51], s[18:19], 0, v[132:133]
	s_mov_b32 m0, s37
	s_nop 0
	global_load_lds_dwordx4 v[50:51], off
	s_barrier
	s_waitcnt lgkmcnt(0)
	s_setprio 3
	s_waitcnt lgkmcnt(0)
	v_mfma_f32_16x16x32_bf16 v[50:53], v[82:85], v[228:231], v[98:101]
	v_mfma_f32_16x16x32_bf16 v[34:37], v[90:93], v[236:239], v[34:37]
	v_mfma_f32_16x16x32_bf16 v[62:65], v[86:89], v[232:235], v[50:53]
	v_mfma_f32_16x16x32_bf16 v[42:45], v[82:85], v[236:239], v[42:45]
	v_mfma_f32_16x16x32_bf16 v[50:53], v[94:97], v[240:243], v[34:37]
	v_mfma_f32_16x16x32_bf16 v[34:37], v[212:215], v[228:231], v[38:41]
	v_mfma_f32_16x16x32_bf16 v[58:61], v[86:89], v[240:243], v[42:45]
	v_mfma_f32_16x16x32_bf16 v[42:45], v[90:93], v[228:231], v[46:49]
	v_mfma_f32_16x16x32_bf16 v[46:49], v[216:219], v[232:235], v[34:37]
	v_mfma_f32_16x16x32_bf16 v[34:37], v[212:215], v[236:239], v[102:105]
	v_mfma_f32_16x16x32_bf16 v[54:57], v[94:97], v[232:235], v[42:45]
	v_mfma_f32_16x16x32_bf16 v[42:45], v[216:219], v[240:243], v[34:37]
	v_mfma_f32_16x16x32_bf16 v[34:37], v[220:223], v[228:231], v[106:109]
	v_mfma_f32_16x16x32_bf16 v[38:41], v[224:227], v[232:235], v[34:37]
	v_mfma_f32_16x16x32_bf16 v[34:37], v[220:223], v[236:239], v[110:113]
	v_mfma_f32_16x16x32_bf16 v[34:37], v[224:227], v[240:243], v[34:37]
	s_setprio 0
	s_add_u32 s18, s17, 0x180
	s_addc_u32 s19, s58, 0
	s_mov_b32 m0, s38
	s_barrier
	ds_read_b128 v[98:101], v136 offset:49152
	ds_read_b128 v[102:105], v136 offset:50176
	ds_read_b128 v[106:109], v136 offset:51200
	ds_read_b128 v[110:113], v136 offset:52224
	ds_read_b128 v[212:215], v136 offset:53248
	ds_read_b128 v[216:219], v136 offset:54272
	ds_read_b128 v[220:223], v136 offset:55296
	ds_read_b128 v[224:227], v136 offset:56320
	s_nop 0
	v_lshl_add_u64 v[66:67], s[18:19], 0, v[130:131]
	global_load_lds_dwordx4 v[66:67], off
	v_lshl_add_u64 v[66:67], s[18:19], 0, v[132:133]
	s_mov_b32 m0, s39
	s_nop 0
	global_load_lds_dwordx4 v[66:67], off
	s_barrier
	s_waitcnt lgkmcnt(0)
	s_setprio 3
	s_waitcnt lgkmcnt(0)
	v_mfma_f32_16x16x32_bf16 v[66:69], v[98:101], v[114:117], v[142:145]
	v_mfma_f32_16x16x32_bf16 v[94:97], v[102:105], v[118:121], v[66:69]
	v_mfma_f32_16x16x32_bf16 v[66:69], v[98:101], v[122:125], v[146:149]
	v_mfma_f32_16x16x32_bf16 v[90:93], v[102:105], v[126:129], v[66:69]
	v_mfma_f32_16x16x32_bf16 v[66:69], v[106:109], v[114:117], v[150:153]
	v_mfma_f32_16x16x32_bf16 v[86:89], v[110:113], v[118:121], v[66:69]
	v_mfma_f32_16x16x32_bf16 v[66:69], v[106:109], v[122:125], v[154:157]
	v_mfma_f32_16x16x32_bf16 v[82:85], v[110:113], v[126:129], v[66:69]
	v_mfma_f32_16x16x32_bf16 v[66:69], v[212:215], v[114:117], v[158:161]
	v_mfma_f32_16x16x32_bf16 v[78:81], v[216:219], v[118:121], v[66:69]
	v_mfma_f32_16x16x32_bf16 v[66:69], v[212:215], v[122:125], v[162:165]
	v_mfma_f32_16x16x32_bf16 v[74:77], v[216:219], v[126:129], v[66:69]
	v_mfma_f32_16x16x32_bf16 v[66:69], v[220:223], v[114:117], v[166:169]
	v_mfma_f32_16x16x32_bf16 v[70:73], v[224:227], v[118:121], v[66:69]
	v_mfma_f32_16x16x32_bf16 v[66:69], v[220:223], v[122:125], v[170:173]
	v_mfma_f32_16x16x32_bf16 v[66:69], v[224:227], v[126:129], v[66:69]
	s_setprio 0
	s_barrier
	s_add_u32 s18, s59, 0x180
	s_addc_u32 s19, s60, 0
	s_mov_b32 m0, s40
	s_nop 0
	v_lshl_add_u64 v[114:115], s[18:19], 0, v[130:131]
	global_load_lds_dwordx4 v[114:115], off
	v_lshl_add_u64 v[114:115], s[18:19], 0, v[132:133]
	s_mov_b32 m0, s41
	s_nop 0
	global_load_lds_dwordx4 v[114:115], off
	s_waitcnt vmcnt(6)
	s_barrier
	s_setprio 3
	v_mfma_f32_16x16x32_bf16 v[114:117], v[98:101], v[228:231], v[174:177]
	v_mfma_f32_16x16x32_bf16 v[98:101], v[98:101], v[236:239], v[178:181]
	v_mfma_f32_16x16x32_bf16 v[122:125], v[102:105], v[240:243], v[98:101]
	v_mfma_f32_16x16x32_bf16 v[98:101], v[106:109], v[228:231], v[182:185]
	v_mfma_f32_16x16x32_bf16 v[118:121], v[110:113], v[232:235], v[98:101]
	v_mfma_f32_16x16x32_bf16 v[98:101], v[106:109], v[236:239], v[186:189]
	v_mfma_f32_16x16x32_bf16 v[126:129], v[102:105], v[232:235], v[114:117]
	v_mfma_f32_16x16x32_bf16 v[114:117], v[110:113], v[240:243], v[98:101]
	v_mfma_f32_16x16x32_bf16 v[98:101], v[212:215], v[228:231], v[190:193]
	v_mfma_f32_16x16x32_bf16 v[110:113], v[216:219], v[232:235], v[98:101]
	v_mfma_f32_16x16x32_bf16 v[98:101], v[212:215], v[236:239], v[194:197]
	v_mfma_f32_16x16x32_bf16 v[106:109], v[216:219], v[240:243], v[98:101]
	v_mfma_f32_16x16x32_bf16 v[98:101], v[220:223], v[228:231], v[198:201]
	v_mfma_f32_16x16x32_bf16 v[102:105], v[224:227], v[232:235], v[98:101]
	v_mfma_f32_16x16x32_bf16 v[98:101], v[220:223], v[236:239], v[202:205]
	v_mfma_f32_16x16x32_bf16 v[98:101], v[224:227], v[240:243], v[98:101]
	s_setprio 0
	s_mov_b32 s61, 0
	s_mov_b64 s[18:19], 0
	s_barrier

.LBB0_467:
	s_mul_hi_i32 s12, s49, 0x2e8ba2e9
	s_lshr_b32 s13, s12, 31
	s_ashr_i32 s12, s12, 5
	s_add_i32 s12, s12, s13
	s_mul_i32 s13, s12, 0xffffff50
	s_add_i32 s13, s13, s49
	s_ashr_i32 s50, s13, 3
	s_lshl_b32 s13, s49, 8
	s_lshl_b32 s12, s12, 11
	s_and_b32 s13, s13, 0x700
	s_or_b32 s12, s12, s13
	s_or_b32 s18, s12, 0x80
	s_ashr_i32 s19, s18, 31
	s_lshl_b32 s16, s50, 8
	s_lshl_b64 s[14:15], s[18:19], 10
	s_lshl_b64 s[18:19], s[18:19], 11
	s_add_u32 s18, s20, s18
	s_addc_u32 s19, s21, s19
	s_ashr_i32 s17, s16, 31
	s_lshl_b64 s[52:53], s[16:17], 11
	s_add_u32 s51, s22, s52
	s_addc_u32 s52, s23, s53
	s_ashr_i32 s13, s12, 31
	s_barrier
	s_barrier
	s_lshl_b64 s[54:55], s[12:13], 11
	ds_read_b128 v[2:5], v137
	ds_read_b128 v[6:9], v137 offset:1024
	ds_read_b128 v[10:13], v137 offset:2048
	ds_read_b128 v[14:17], v137 offset:3072
	s_add_u32 s13, s20, s54
	s_addc_u32 s53, s21, s55
	s_bitset1_b32 s16, 7
	s_ashr_i32 s17, s16, 31
	s_lshl_b64 s[16:17], s[16:17], 11
	s_add_u32 s54, s22, s16
	s_addc_u32 s55, s23, s17
	ds_read_b128 v[18:21], v136 offset:7168
	ds_read_b128 v[22:25], v136 offset:6144
	ds_read_b128 v[26:29], v136 offset:5120
	ds_read_b128 v[30:33], v136 offset:4096
	ds_read_b128 v[34:37], v136 offset:3072
	ds_read_b128 v[38:41], v136 offset:2048
	ds_read_b128 v[42:45], v136 offset:1024
	ds_read_b128 v[46:49], v136
	s_waitcnt lgkmcnt(8)
	s_barrier
	s_waitcnt lgkmcnt(0)
	s_setprio 3
	s_waitcnt lgkmcnt(0)
	v_mfma_f32_16x16x32_bf16 v[50:53], v[46:49], v[2:5], 0
	v_mfma_f32_16x16x32_bf16 v[54:57], v[46:49], v[10:13], 0
	v_mfma_f32_16x16x32_bf16 v[58:61], v[38:41], v[2:5], 0
	v_mfma_f32_16x16x32_bf16 v[62:65], v[38:41], v[10:13], 0
	v_mfma_f32_16x16x32_bf16 v[66:69], v[30:33], v[2:5], 0
	v_mfma_f32_16x16x32_bf16 v[70:73], v[30:33], v[10:13], 0
	v_mfma_f32_16x16x32_bf16 v[74:77], v[22:25], v[2:5], 0
	v_mfma_f32_16x16x32_bf16 v[78:81], v[22:25], v[10:13], 0
	v_mfma_f32_16x16x32_bf16 v[50:53], v[42:45], v[6:9], v[50:53]
	v_mfma_f32_16x16x32_bf16 v[54:57], v[42:45], v[14:17], v[54:57]
	v_mfma_f32_16x16x32_bf16 v[58:61], v[34:37], v[6:9], v[58:61]
	v_mfma_f32_16x16x32_bf16 v[62:65], v[34:37], v[14:17], v[62:65]
	v_mfma_f32_16x16x32_bf16 v[66:69], v[26:29], v[6:9], v[66:69]
	v_mfma_f32_16x16x32_bf16 v[70:73], v[26:29], v[14:17], v[70:73]
	v_mfma_f32_16x16x32_bf16 v[74:77], v[18:21], v[6:9], v[74:77]
	v_mfma_f32_16x16x32_bf16 v[78:81], v[18:21], v[14:17], v[78:81]
	s_setprio 0
	s_barrier
	s_add_u32 s16, s51, 0x100
	s_addc_u32 s17, s52, 0
	s_mov_b32 m0, s26
	ds_read_b128 v[82:85], v137 offset:16384
	ds_read_b128 v[86:89], v137 offset:17408
	ds_read_b128 v[90:93], v137 offset:18432
	ds_read_b128 v[94:97], v137 offset:19456
	s_nop 0
	v_lshl_add_u64 v[98:99], s[16:17], 0, v[130:131]
	global_load_lds_dwordx4 v[98:99], off
	v_lshl_add_u64 v[98:99], s[16:17], 0, v[132:133]
	s_mov_b32 m0, s27
	s_nop 0
	global_load_lds_dwordx4 v[98:99], off
	s_barrier
	s_waitcnt lgkmcnt(0)
	s_setprio 3
	s_waitcnt lgkmcnt(0)
	v_mfma_f32_16x16x32_bf16 v[98:101], v[46:49], v[82:85], 0
	v_mfma_f32_16x16x32_bf16 v[46:49], v[46:49], v[90:93], 0
	v_mfma_f32_16x16x32_bf16 v[98:101], v[42:45], v[86:89], v[98:101]
	v_mfma_f32_16x16x32_bf16 v[42:45], v[42:45], v[94:97], v[46:49]
	v_mfma_f32_16x16x32_bf16 v[46:49], v[38:41], v[82:85], 0
	v_mfma_f32_16x16x32_bf16 v[38:41], v[38:41], v[90:93], 0
	v_mfma_f32_16x16x32_bf16 v[46:49], v[34:37], v[86:89], v[46:49]
	v_mfma_f32_16x16x32_bf16 v[34:37], v[34:37], v[94:97], v[38:41]
	v_mfma_f32_16x16x32_bf16 v[38:41], v[30:33], v[82:85], 0
	v_mfma_f32_16x16x32_bf16 v[30:33], v[30:33], v[90:93], 0
	v_mfma_f32_16x16x32_bf16 v[38:41], v[26:29], v[86:89], v[38:41]
	v_mfma_f32_16x16x32_bf16 v[102:105], v[26:29], v[94:97], v[30:33]
	v_mfma_f32_16x16x32_bf16 v[26:29], v[22:25], v[82:85], 0
	v_mfma_f32_16x16x32_bf16 v[22:25], v[22:25], v[90:93], 0
	v_mfma_f32_16x16x32_bf16 v[106:109], v[18:21], v[86:89], v[26:29]
	v_mfma_f32_16x16x32_bf16 v[110:113], v[18:21], v[94:97], v[22:25]
	s_setprio 0
	s_add_u32 s16, s13, 0x100
	s_addc_u32 s17, s53, 0
	s_mov_b32 m0, s25
	s_barrier
	ds_read_b128 v[18:21], v136 offset:16384
	ds_read_b128 v[22:25], v136 offset:17408
	ds_read_b128 v[26:29], v136 offset:18432
	ds_read_b128 v[30:33], v136 offset:19456
	ds_read_b128 v[114:117], v136 offset:20480
	ds_read_b128 v[118:121], v136 offset:21504
	ds_read_b128 v[122:125], v136 offset:22528
	ds_read_b128 v[126:129], v136 offset:23552
	s_nop 0
	v_lshl_add_u64 v[134:135], s[16:17], 0, v[130:131]
	global_load_lds_dwordx4 v[134:135], off
	v_lshl_add_u64 v[134:135], s[16:17], 0, v[132:133]
	s_mov_b32 m0, s28
	s_nop 0
	global_load_lds_dwordx4 v[134:135], off
	s_barrier
	s_waitcnt lgkmcnt(0)
	s_setprio 3
	s_waitcnt lgkmcnt(0)
	v_mfma_f32_16x16x32_bf16 v[142:145], v[18:21], v[2:5], 0
	v_mfma_f32_16x16x32_bf16 v[150:153], v[26:29], v[2:5], 0
	v_mfma_f32_16x16x32_bf16 v[158:161], v[114:117], v[2:5], 0
	v_mfma_f32_16x16x32_bf16 v[2:5], v[122:125], v[2:5], 0
	v_mfma_f32_16x16x32_bf16 v[146:149], v[18:21], v[10:13], 0
	v_mfma_f32_16x16x32_bf16 v[154:157], v[26:29], v[10:13], 0
	v_mfma_f32_16x16x32_bf16 v[162:165], v[114:117], v[10:13], 0
	v_mfma_f32_16x16x32_bf16 v[166:169], v[126:129], v[6:9], v[2:5]
	v_mfma_f32_16x16x32_bf16 v[2:5], v[122:125], v[10:13], 0
	v_mfma_f32_16x16x32_bf16 v[142:145], v[22:25], v[6:9], v[142:145]
	v_mfma_f32_16x16x32_bf16 v[146:149], v[22:25], v[14:17], v[146:149]
	v_mfma_f32_16x16x32_bf16 v[150:153], v[30:33], v[6:9], v[150:153]
	v_mfma_f32_16x16x32_bf16 v[154:157], v[30:33], v[14:17], v[154:157]
	v_mfma_f32_16x16x32_bf16 v[158:161], v[118:121], v[6:9], v[158:161]
	v_mfma_f32_16x16x32_bf16 v[162:165], v[118:121], v[14:17], v[162:165]
	v_mfma_f32_16x16x32_bf16 v[170:173], v[126:129], v[14:17], v[2:5]
	s_setprio 0
	s_barrier
	s_add_u32 s16, s54, 0x100
	s_addc_u32 s17, s55, 0
	s_mov_b32 m0, s29
	s_nop 0
	v_lshl_add_u64 v[2:3], s[16:17], 0, v[130:131]
	global_load_lds_dwordx4 v[2:3], off
	v_lshl_add_u64 v[2:3], s[16:17], 0, v[132:133]
	s_mov_b32 m0, s30
	s_nop 0
	global_load_lds_dwordx4 v[2:3], off
	s_waitcnt vmcnt(14)
	s_barrier
	s_setprio 3
	v_mfma_f32_16x16x32_bf16 v[2:5], v[18:21], v[82:85], 0
	v_mfma_f32_16x16x32_bf16 v[174:177], v[22:25], v[86:89], v[2:5]
	v_mfma_f32_16x16x32_bf16 v[2:5], v[18:21], v[90:93], 0
	v_mfma_f32_16x16x32_bf16 v[178:181], v[22:25], v[94:97], v[2:5]
	v_mfma_f32_16x16x32_bf16 v[2:5], v[26:29], v[82:85], 0
	v_mfma_f32_16x16x32_bf16 v[182:185], v[30:33], v[86:89], v[2:5]
	v_mfma_f32_16x16x32_bf16 v[2:5], v[26:29], v[90:93], 0
	v_mfma_f32_16x16x32_bf16 v[186:189], v[30:33], v[94:97], v[2:5]
	v_mfma_f32_16x16x32_bf16 v[2:5], v[114:117], v[82:85], 0
	v_mfma_f32_16x16x32_bf16 v[190:193], v[118:121], v[86:89], v[2:5]
	v_mfma_f32_16x16x32_bf16 v[2:5], v[114:117], v[90:93], 0
	v_mfma_f32_16x16x32_bf16 v[194:197], v[118:121], v[94:97], v[2:5]
	v_mfma_f32_16x16x32_bf16 v[2:5], v[122:125], v[82:85], 0
	v_mfma_f32_16x16x32_bf16 v[198:201], v[126:129], v[86:89], v[2:5]
	v_mfma_f32_16x16x32_bf16 v[2:5], v[122:125], v[90:93], 0
	v_mfma_f32_16x16x32_bf16 v[202:205], v[126:129], v[94:97], v[2:5]
	s_setprio 0
	s_barrier
	ds_read_b128 v[114:117], v137 offset:32768
	ds_read_b128 v[118:121], v137 offset:33792
	ds_read_b128 v[122:125], v137 offset:34816
	ds_read_b128 v[126:129], v137 offset:35840
	s_add_u32 s16, s18, 0x100
	s_addc_u32 s17, s19, 0
	s_mov_b32 m0, s31
	ds_read_b128 v[82:85], v136 offset:32768
	ds_read_b128 v[86:89], v136 offset:33792
	ds_read_b128 v[90:93], v136 offset:34816
	ds_read_b128 v[94:97], v136 offset:35840
	ds_read_b128 v[216:219], v136 offset:36864
	ds_read_b128 v[220:223], v136 offset:37888
	ds_read_b128 v[224:227], v136 offset:38912
	ds_read_b128 v[228:231], v136 offset:39936
	s_nop 0
	v_lshl_add_u64 v[2:3], s[16:17], 0, v[130:131]
	global_load_lds_dwordx4 v[2:3], off
	v_lshl_add_u64 v[2:3], s[16:17], 0, v[132:133]
	s_mov_b32 m0, s33
	s_nop 0
	global_load_lds_dwordx4 v[2:3], off
	s_waitcnt lgkmcnt(8)
	s_barrier
	s_waitcnt lgkmcnt(0)
	s_setprio 3
	s_waitcnt lgkmcnt(0)
	v_mfma_f32_16x16x32_bf16 v[2:5], v[82:85], v[114:117], v[50:53]
	v_mfma_f32_16x16x32_bf16 v[30:33], v[86:89], v[118:121], v[2:5]
	v_mfma_f32_16x16x32_bf16 v[2:5], v[82:85], v[122:125], v[54:57]
	v_mfma_f32_16x16x32_bf16 v[26:29], v[86:89], v[126:129], v[2:5]
	v_mfma_f32_16x16x32_bf16 v[2:5], v[90:93], v[114:117], v[58:61]
	v_mfma_f32_16x16x32_bf16 v[22:25], v[94:97], v[118:121], v[2:5]
	v_mfma_f32_16x16x32_bf16 v[2:5], v[90:93], v[122:125], v[62:65]
	v_mfma_f32_16x16x32_bf16 v[18:21], v[94:97], v[126:129], v[2:5]
	v_mfma_f32_16x16x32_bf16 v[2:5], v[216:219], v[114:117], v[66:69]
	v_mfma_f32_16x16x32_bf16 v[14:17], v[220:223], v[118:121], v[2:5]
	v_mfma_f32_16x16x32_bf16 v[2:5], v[216:219], v[122:125], v[70:73]
	v_mfma_f32_16x16x32_bf16 v[10:13], v[220:223], v[126:129], v[2:5]
	v_mfma_f32_16x16x32_bf16 v[2:5], v[224:227], v[114:117], v[74:77]
	v_mfma_f32_16x16x32_bf16 v[6:9], v[228:231], v[118:121], v[2:5]
	v_mfma_f32_16x16x32_bf16 v[2:5], v[224:227], v[122:125], v[78:81]
	v_mfma_f32_16x16x32_bf16 v[2:5], v[228:231], v[126:129], v[2:5]
	s_setprio 0
	s_barrier
	s_add_u32 s16, s51, 0x180
	s_addc_u32 s17, s52, 0
	s_mov_b32 m0, s34
	ds_read_b128 v[232:235], v137 offset:49152
	ds_read_b128 v[236:239], v137 offset:50176
	ds_read_b128 v[240:243], v137 offset:51200
	ds_read_b128 v[244:247], v137 offset:52224
	s_nop 0
	v_lshl_add_u64 v[50:51], s[16:17], 0, v[130:131]
	global_load_lds_dwordx4 v[50:51], off
	v_lshl_add_u64 v[50:51], s[16:17], 0, v[132:133]
	s_mov_b32 m0, s35
	s_nop 0
	global_load_lds_dwordx4 v[50:51], off
	s_barrier
	s_waitcnt lgkmcnt(0)
	s_setprio 3
	s_waitcnt lgkmcnt(0)
	v_mfma_f32_16x16x32_bf16 v[50:53], v[82:85], v[232:235], v[98:101]
	v_mfma_f32_16x16x32_bf16 v[34:37], v[90:93], v[240:243], v[34:37]
	v_mfma_f32_16x16x32_bf16 v[62:65], v[86:89], v[236:239], v[50:53]
	v_mfma_f32_16x16x32_bf16 v[42:45], v[82:85], v[240:243], v[42:45]
	v_mfma_f32_16x16x32_bf16 v[50:53], v[94:97], v[244:247], v[34:37]
	v_mfma_f32_16x16x32_bf16 v[34:37], v[216:219], v[232:235], v[38:41]
	v_mfma_f32_16x16x32_bf16 v[58:61], v[86:89], v[244:247], v[42:45]
	v_mfma_f32_16x16x32_bf16 v[42:45], v[90:93], v[232:235], v[46:49]
	v_mfma_f32_16x16x32_bf16 v[46:49], v[220:223], v[236:239], v[34:37]
	v_mfma_f32_16x16x32_bf16 v[34:37], v[216:219], v[240:243], v[102:105]
	v_mfma_f32_16x16x32_bf16 v[54:57], v[94:97], v[236:239], v[42:45]
	v_mfma_f32_16x16x32_bf16 v[42:45], v[220:223], v[244:247], v[34:37]
	v_mfma_f32_16x16x32_bf16 v[34:37], v[224:227], v[232:235], v[106:109]
	v_mfma_f32_16x16x32_bf16 v[38:41], v[228:231], v[236:239], v[34:37]
	v_mfma_f32_16x16x32_bf16 v[34:37], v[224:227], v[240:243], v[110:113]
	v_mfma_f32_16x16x32_bf16 v[34:37], v[228:231], v[244:247], v[34:37]
	s_setprio 0
	s_add_u32 s16, s13, 0x180
	s_addc_u32 s17, s53, 0
	s_mov_b32 m0, s36
	s_barrier
	ds_read_b128 v[98:101], v136 offset:49152
	ds_read_b128 v[102:105], v136 offset:50176
	ds_read_b128 v[106:109], v136 offset:51200
	ds_read_b128 v[110:113], v136 offset:52224
	ds_read_b128 v[216:219], v136 offset:53248
	ds_read_b128 v[220:223], v136 offset:54272
	ds_read_b128 v[224:227], v136 offset:55296
	ds_read_b128 v[228:231], v136 offset:56320
	s_nop 0
	v_lshl_add_u64 v[66:67], s[16:17], 0, v[130:131]
	global_load_lds_dwordx4 v[66:67], off
	v_lshl_add_u64 v[66:67], s[16:17], 0, v[132:133]
	s_mov_b32 m0, s37
	s_nop 0
	global_load_lds_dwordx4 v[66:67], off
	s_barrier
	s_waitcnt lgkmcnt(0)
	s_setprio 3
	s_waitcnt lgkmcnt(0)
	v_mfma_f32_16x16x32_bf16 v[66:69], v[98:101], v[114:117], v[142:145]
	v_mfma_f32_16x16x32_bf16 v[94:97], v[102:105], v[118:121], v[66:69]
	v_mfma_f32_16x16x32_bf16 v[66:69], v[98:101], v[122:125], v[146:149]
	v_mfma_f32_16x16x32_bf16 v[90:93], v[102:105], v[126:129], v[66:69]
	v_mfma_f32_16x16x32_bf16 v[66:69], v[106:109], v[114:117], v[150:153]
	v_mfma_f32_16x16x32_bf16 v[86:89], v[110:113], v[118:121], v[66:69]
	v_mfma_f32_16x16x32_bf16 v[66:69], v[106:109], v[122:125], v[154:157]
	v_mfma_f32_16x16x32_bf16 v[82:85], v[110:113], v[126:129], v[66:69]
	v_mfma_f32_16x16x32_bf16 v[66:69], v[216:219], v[114:117], v[158:161]
	v_mfma_f32_16x16x32_bf16 v[78:81], v[220:223], v[118:121], v[66:69]
	v_mfma_f32_16x16x32_bf16 v[66:69], v[216:219], v[122:125], v[162:165]
	v_mfma_f32_16x16x32_bf16 v[74:77], v[220:223], v[126:129], v[66:69]
	v_mfma_f32_16x16x32_bf16 v[66:69], v[224:227], v[114:117], v[166:169]
	v_mfma_f32_16x16x32_bf16 v[70:73], v[228:231], v[118:121], v[66:69]
	v_mfma_f32_16x16x32_bf16 v[66:69], v[224:227], v[122:125], v[170:173]
	v_mfma_f32_16x16x32_bf16 v[66:69], v[228:231], v[126:129], v[66:69]
	s_setprio 0
	s_barrier
	s_add_u32 s16, s54, 0x180
	s_addc_u32 s17, s55, 0
	s_mov_b32 m0, s38
	s_nop 0
	v_lshl_add_u64 v[114:115], s[16:17], 0, v[130:131]
	global_load_lds_dwordx4 v[114:115], off
	v_lshl_add_u64 v[114:115], s[16:17], 0, v[132:133]
	s_mov_b32 m0, s39
	s_nop 0
	global_load_lds_dwordx4 v[114:115], off
	s_waitcnt vmcnt(6)
	s_barrier
	s_setprio 3
	v_mfma_f32_16x16x32_bf16 v[114:117], v[98:101], v[232:235], v[174:177]
	v_mfma_f32_16x16x32_bf16 v[98:101], v[98:101], v[240:243], v[178:181]
	v_mfma_f32_16x16x32_bf16 v[122:125], v[102:105], v[244:247], v[98:101]
	v_mfma_f32_16x16x32_bf16 v[98:101], v[106:109], v[232:235], v[182:185]
	v_mfma_f32_16x16x32_bf16 v[118:121], v[110:113], v[236:239], v[98:101]
	v_mfma_f32_16x16x32_bf16 v[98:101], v[106:109], v[240:243], v[186:189]
	v_mfma_f32_16x16x32_bf16 v[126:129], v[102:105], v[236:239], v[114:117]
	v_mfma_f32_16x16x32_bf16 v[114:117], v[110:113], v[244:247], v[98:101]
	v_mfma_f32_16x16x32_bf16 v[98:101], v[216:219], v[232:235], v[190:193]
	v_mfma_f32_16x16x32_bf16 v[110:113], v[220:223], v[236:239], v[98:101]
	v_mfma_f32_16x16x32_bf16 v[98:101], v[216:219], v[240:243], v[194:197]
	v_mfma_f32_16x16x32_bf16 v[106:109], v[220:223], v[244:247], v[98:101]
	v_mfma_f32_16x16x32_bf16 v[98:101], v[224:227], v[232:235], v[198:201]
	v_mfma_f32_16x16x32_bf16 v[102:105], v[228:231], v[236:239], v[98:101]
	v_mfma_f32_16x16x32_bf16 v[98:101], v[224:227], v[240:243], v[202:205]
	v_mfma_f32_16x16x32_bf16 v[98:101], v[228:231], v[244:247], v[98:101]
	s_setprio 0
	s_mov_b32 s56, 0
	s_mov_b64 s[16:17], 0
	s_barrier
